# in-proj sample-row GEMM K-part rewritten: two k-steps of loads in flight, counted vmcnt, accumulate in place
# speedup vs baseline: 1.0031x; 1.0013x over previous
.LBB0_871:
	s_and_b32 s5, s36, 0xffffffc0
	v_or_b32_e32 v144, s5, v172
	v_ashrrev_i32_e32 v145, 31, v144
	v_lshlrev_b64 v[146:147], 11, v[144:145]
	v_lshl_add_u64 v[170:171], v[140:141], 0, v[146:147]
	s_and_b32 s4, s18, 31
	v_add_co_u32_e32 v152, vcc, 0x8000, v170
	s_mulk_i32 s4, 0x70
	s_nop 0
	v_addc_co_u32_e32 v153, vcc, 0, v171, vcc
	v_or_b32_e32 v0, s4, v172
	v_add_co_u32_e32 v150, vcc, 0x10000, v170
	v_lshlrev_b32_e32 v160, 11, v0
	s_mov_b64 s[38:39], vcc
	v_add_co_u32_e32 v148, vcc, 0x18000, v170
	v_lshl_add_u64 v[168:169], v[142:143], 0, v[160:161]
	s_nop 0
	v_addc_co_u32_e32 v149, vcc, 0, v171, vcc
	s_mov_b32 s5, 0x8000
	v_add_co_u32_e32 v158, vcc, s5, v168
	v_add_co_u32_e32 v152, vcc, 0x8000, v170
	s_nop 1
	v_addc_co_u32_e32 v153, vcc, 0, v171, vcc
	v_add_co_u32_e32 v150, vcc, 0x10000, v170
	s_nop 1
	v_addc_co_u32_e32 v151, vcc, 0, v171, vcc
	v_add_co_u32_e32 v148, vcc, 0x18000, v170
	s_nop 1
	v_addc_co_u32_e32 v149, vcc, 0, v171, vcc
	v_add_co_u32_e32 v158, vcc, 0x8000, v168
	s_nop 1
	v_addc_co_u32_e32 v159, vcc, 0, v169, vcc
	v_add_co_u32_e32 v162, vcc, 0x10000, v168
	s_nop 1
	v_addc_co_u32_e32 v163, vcc, 0, v169, vcc
	v_add_co_u32_e32 v164, vcc, 0x18000, v168
	s_nop 1
	v_addc_co_u32_e32 v165, vcc, 0, v169, vcc
	v_add_co_u32_e32 v166, vcc, 0x20000, v168
	s_nop 1
	v_addc_co_u32_e32 v167, vcc, 0, v169, vcc
	v_add_co_u32_e32 v156, vcc, 0x28000, v168
	s_nop 1
	v_addc_co_u32_e32 v157, vcc, 0, v169, vcc
	v_add_co_u32_e32 v154, vcc, 0x30000, v168
	s_nop 1
	v_addc_co_u32_e32 v155, vcc, 0, v169, vcc
	global_load_dwordx4 v[84:87], v[170:171], off
	global_load_dwordx4 v[92:95], v[152:153], off
	global_load_dwordx4 v[112:115], v[150:151], off
	global_load_dwordx4 v[124:127], v[148:149], off
	global_load_dwordx4 v[128:131], v[168:169], off
	global_load_dwordx4 v[136:139], v[158:159], off
	global_load_dwordx4 v[176:179], v[162:163], off
	global_load_dwordx4 v[180:183], v[164:165], off
	global_load_dwordx4 v[184:187], v[166:167], off
	global_load_dwordx4 v[188:191], v[156:157], off
	global_load_dwordx4 v[194:197], v[154:155], off
	global_load_dwordx4 v[116:119], v[170:171], off offset:64
	global_load_dwordx4 v[198:201], v[152:153], off offset:64
	global_load_dwordx4 v[202:205], v[150:151], off offset:64
	global_load_dwordx4 v[206:209], v[148:149], off offset:64
	global_load_dwordx4 v[210:213], v[168:169], off offset:64
	global_load_dwordx4 v[214:217], v[158:159], off offset:64
	global_load_dwordx4 v[218:221], v[162:163], off offset:64
	global_load_dwordx4 v[222:225], v[164:165], off offset:64
	global_load_dwordx4 v[226:229], v[166:167], off offset:64
	global_load_dwordx4 v[230:233], v[156:157], off offset:64
	global_load_dwordx4 v[234:237], v[154:155], off offset:64
	s_waitcnt vmcnt(11)
	v_mfma_f32_16x16x32_bf16 v[88:91], v[128:131], v[84:87], 0
	v_mfma_f32_16x16x32_bf16 v[120:123], v[136:139], v[84:87], 0
	v_mfma_f32_16x16x32_bf16 v[132:135], v[176:179], v[84:87], 0
	v_mfma_f32_16x16x32_bf16 v[96:99], v[180:183], v[84:87], 0
	v_mfma_f32_16x16x32_bf16 v[100:103], v[184:187], v[84:87], 0
	v_mfma_f32_16x16x32_bf16 v[104:107], v[188:191], v[84:87], 0
	v_mfma_f32_16x16x32_bf16 v[108:111], v[194:197], v[84:87], 0
	v_mfma_f32_16x16x32_bf16 v[56:59], v[128:131], v[92:95], 0
	v_mfma_f32_16x16x32_bf16 v[60:63], v[136:139], v[92:95], 0
	v_mfma_f32_16x16x32_bf16 v[64:67], v[176:179], v[92:95], 0
	v_mfma_f32_16x16x32_bf16 v[68:71], v[180:183], v[92:95], 0
	v_mfma_f32_16x16x32_bf16 v[72:75], v[184:187], v[92:95], 0
	v_mfma_f32_16x16x32_bf16 v[76:79], v[188:191], v[92:95], 0
	v_mfma_f32_16x16x32_bf16 v[80:83], v[194:197], v[92:95], 0
	v_mfma_f32_16x16x32_bf16 v[28:31], v[128:131], v[112:115], 0
	v_mfma_f32_16x16x32_bf16 v[32:35], v[136:139], v[112:115], 0
	v_mfma_f32_16x16x32_bf16 v[36:39], v[176:179], v[112:115], 0
	v_mfma_f32_16x16x32_bf16 v[40:43], v[180:183], v[112:115], 0
	v_mfma_f32_16x16x32_bf16 v[44:47], v[184:187], v[112:115], 0
	v_mfma_f32_16x16x32_bf16 v[48:51], v[188:191], v[112:115], 0
	v_mfma_f32_16x16x32_bf16 v[52:55], v[194:197], v[112:115], 0
	v_mfma_f32_16x16x32_bf16 v[0:3], v[128:131], v[124:127], 0
	v_mfma_f32_16x16x32_bf16 v[4:7], v[136:139], v[124:127], 0
	v_mfma_f32_16x16x32_bf16 v[8:11], v[176:179], v[124:127], 0
	v_mfma_f32_16x16x32_bf16 v[12:15], v[180:183], v[124:127], 0
	v_mfma_f32_16x16x32_bf16 v[16:19], v[184:187], v[124:127], 0
	v_mfma_f32_16x16x32_bf16 v[20:23], v[188:191], v[124:127], 0
	v_mfma_f32_16x16x32_bf16 v[24:27], v[194:197], v[124:127], 0
	global_load_dwordx4 v[84:87], v[170:171], off offset:128
	global_load_dwordx4 v[92:95], v[152:153], off offset:128
	global_load_dwordx4 v[112:115], v[150:151], off offset:128
	global_load_dwordx4 v[124:127], v[148:149], off offset:128
	global_load_dwordx4 v[128:131], v[168:169], off offset:128
	global_load_dwordx4 v[136:139], v[158:159], off offset:128
	global_load_dwordx4 v[176:179], v[162:163], off offset:128
	global_load_dwordx4 v[180:183], v[164:165], off offset:128
	global_load_dwordx4 v[184:187], v[166:167], off offset:128
	global_load_dwordx4 v[188:191], v[156:157], off offset:128
	global_load_dwordx4 v[194:197], v[154:155], off offset:128
	s_waitcnt vmcnt(11)
	v_mfma_f32_16x16x32_bf16 v[88:91], v[210:213], v[116:119], v[88:91]
	v_mfma_f32_16x16x32_bf16 v[120:123], v[214:217], v[116:119], v[120:123]
	v_mfma_f32_16x16x32_bf16 v[132:135], v[218:221], v[116:119], v[132:135]
	v_mfma_f32_16x16x32_bf16 v[96:99], v[222:225], v[116:119], v[96:99]
	v_mfma_f32_16x16x32_bf16 v[100:103], v[226:229], v[116:119], v[100:103]
	v_mfma_f32_16x16x32_bf16 v[104:107], v[230:233], v[116:119], v[104:107]
	v_mfma_f32_16x16x32_bf16 v[108:111], v[234:237], v[116:119], v[108:111]
	v_mfma_f32_16x16x32_bf16 v[56:59], v[210:213], v[198:201], v[56:59]
	v_mfma_f32_16x16x32_bf16 v[60:63], v[214:217], v[198:201], v[60:63]
	v_mfma_f32_16x16x32_bf16 v[64:67], v[218:221], v[198:201], v[64:67]
	v_mfma_f32_16x16x32_bf16 v[68:71], v[222:225], v[198:201], v[68:71]
	v_mfma_f32_16x16x32_bf16 v[72:75], v[226:229], v[198:201], v[72:75]
	v_mfma_f32_16x16x32_bf16 v[76:79], v[230:233], v[198:201], v[76:79]
	v_mfma_f32_16x16x32_bf16 v[80:83], v[234:237], v[198:201], v[80:83]
	v_mfma_f32_16x16x32_bf16 v[28:31], v[210:213], v[202:205], v[28:31]
	v_mfma_f32_16x16x32_bf16 v[32:35], v[214:217], v[202:205], v[32:35]
	v_mfma_f32_16x16x32_bf16 v[36:39], v[218:221], v[202:205], v[36:39]
	v_mfma_f32_16x16x32_bf16 v[40:43], v[222:225], v[202:205], v[40:43]
	v_mfma_f32_16x16x32_bf16 v[44:47], v[226:229], v[202:205], v[44:47]
	v_mfma_f32_16x16x32_bf16 v[48:51], v[230:233], v[202:205], v[48:51]
	v_mfma_f32_16x16x32_bf16 v[52:55], v[234:237], v[202:205], v[52:55]
	v_mfma_f32_16x16x32_bf16 v[0:3], v[210:213], v[206:209], v[0:3]
	v_mfma_f32_16x16x32_bf16 v[4:7], v[214:217], v[206:209], v[4:7]
	v_mfma_f32_16x16x32_bf16 v[8:11], v[218:221], v[206:209], v[8:11]
	v_mfma_f32_16x16x32_bf16 v[12:15], v[222:225], v[206:209], v[12:15]
	v_mfma_f32_16x16x32_bf16 v[16:19], v[226:229], v[206:209], v[16:19]
	v_mfma_f32_16x16x32_bf16 v[20:23], v[230:233], v[206:209], v[20:23]
	v_mfma_f32_16x16x32_bf16 v[24:27], v[234:237], v[206:209], v[24:27]
	global_load_dwordx4 v[116:119], v[170:171], off offset:192
	global_load_dwordx4 v[198:201], v[152:153], off offset:192
	global_load_dwordx4 v[202:205], v[150:151], off offset:192
	global_load_dwordx4 v[206:209], v[148:149], off offset:192
	global_load_dwordx4 v[210:213], v[168:169], off offset:192
	global_load_dwordx4 v[214:217], v[158:159], off offset:192
	global_load_dwordx4 v[218:221], v[162:163], off offset:192
	global_load_dwordx4 v[222:225], v[164:165], off offset:192
	global_load_dwordx4 v[226:229], v[166:167], off offset:192
	global_load_dwordx4 v[230:233], v[156:157], off offset:192
	global_load_dwordx4 v[234:237], v[154:155], off offset:192
	s_waitcnt vmcnt(11)
	v_mfma_f32_16x16x32_bf16 v[88:91], v[128:131], v[84:87], v[88:91]
	v_mfma_f32_16x16x32_bf16 v[120:123], v[136:139], v[84:87], v[120:123]
	v_mfma_f32_16x16x32_bf16 v[132:135], v[176:179], v[84:87], v[132:135]
	v_mfma_f32_16x16x32_bf16 v[96:99], v[180:183], v[84:87], v[96:99]
	v_mfma_f32_16x16x32_bf16 v[100:103], v[184:187], v[84:87], v[100:103]
	v_mfma_f32_16x16x32_bf16 v[104:107], v[188:191], v[84:87], v[104:107]
	v_mfma_f32_16x16x32_bf16 v[108:111], v[194:197], v[84:87], v[108:111]
	v_mfma_f32_16x16x32_bf16 v[56:59], v[128:131], v[92:95], v[56:59]
	v_mfma_f32_16x16x32_bf16 v[60:63], v[136:139], v[92:95], v[60:63]
	v_mfma_f32_16x16x32_bf16 v[64:67], v[176:179], v[92:95], v[64:67]
	v_mfma_f32_16x16x32_bf16 v[68:71], v[180:183], v[92:95], v[68:71]
	v_mfma_f32_16x16x32_bf16 v[72:75], v[184:187], v[92:95], v[72:75]
	v_mfma_f32_16x16x32_bf16 v[76:79], v[188:191], v[92:95], v[76:79]
	v_mfma_f32_16x16x32_bf16 v[80:83], v[194:197], v[92:95], v[80:83]
	v_mfma_f32_16x16x32_bf16 v[28:31], v[128:131], v[112:115], v[28:31]
	v_mfma_f32_16x16x32_bf16 v[32:35], v[136:139], v[112:115], v[32:35]
	v_mfma_f32_16x16x32_bf16 v[36:39], v[176:179], v[112:115], v[36:39]
	v_mfma_f32_16x16x32_bf16 v[40:43], v[180:183], v[112:115], v[40:43]
	v_mfma_f32_16x16x32_bf16 v[44:47], v[184:187], v[112:115], v[44:47]
	v_mfma_f32_16x16x32_bf16 v[48:51], v[188:191], v[112:115], v[48:51]
	v_mfma_f32_16x16x32_bf16 v[52:55], v[194:197], v[112:115], v[52:55]
	v_mfma_f32_16x16x32_bf16 v[0:3], v[128:131], v[124:127], v[0:3]
	v_mfma_f32_16x16x32_bf16 v[4:7], v[136:139], v[124:127], v[4:7]
	v_mfma_f32_16x16x32_bf16 v[8:11], v[176:179], v[124:127], v[8:11]
	v_mfma_f32_16x16x32_bf16 v[12:15], v[180:183], v[124:127], v[12:15]
	v_mfma_f32_16x16x32_bf16 v[16:19], v[184:187], v[124:127], v[16:19]
	v_mfma_f32_16x16x32_bf16 v[20:23], v[188:191], v[124:127], v[20:23]
	v_mfma_f32_16x16x32_bf16 v[24:27], v[194:197], v[124:127], v[24:27]
	s_waitcnt vmcnt(0)
	v_mfma_f32_16x16x32_bf16 v[88:91], v[210:213], v[116:119], v[88:91]
	v_mfma_f32_16x16x32_bf16 v[120:123], v[214:217], v[116:119], v[120:123]
	v_mfma_f32_16x16x32_bf16 v[132:135], v[218:221], v[116:119], v[132:135]
	v_mfma_f32_16x16x32_bf16 v[96:99], v[222:225], v[116:119], v[96:99]
	v_mfma_f32_16x16x32_bf16 v[100:103], v[226:229], v[116:119], v[100:103]
	v_mfma_f32_16x16x32_bf16 v[104:107], v[230:233], v[116:119], v[104:107]
	v_mfma_f32_16x16x32_bf16 v[108:111], v[234:237], v[116:119], v[108:111]
	v_mfma_f32_16x16x32_bf16 v[56:59], v[210:213], v[198:201], v[56:59]
	v_mfma_f32_16x16x32_bf16 v[60:63], v[214:217], v[198:201], v[60:63]
	v_mfma_f32_16x16x32_bf16 v[64:67], v[218:221], v[198:201], v[64:67]
	v_mfma_f32_16x16x32_bf16 v[68:71], v[222:225], v[198:201], v[68:71]
	v_mfma_f32_16x16x32_bf16 v[72:75], v[226:229], v[198:201], v[72:75]
	v_mfma_f32_16x16x32_bf16 v[76:79], v[230:233], v[198:201], v[76:79]
	v_mfma_f32_16x16x32_bf16 v[80:83], v[234:237], v[198:201], v[80:83]
	v_mfma_f32_16x16x32_bf16 v[28:31], v[210:213], v[202:205], v[28:31]
	v_mfma_f32_16x16x32_bf16 v[32:35], v[214:217], v[202:205], v[32:35]
	v_mfma_f32_16x16x32_bf16 v[36:39], v[218:221], v[202:205], v[36:39]
	v_mfma_f32_16x16x32_bf16 v[40:43], v[222:225], v[202:205], v[40:43]
	v_mfma_f32_16x16x32_bf16 v[44:47], v[226:229], v[202:205], v[44:47]
	v_mfma_f32_16x16x32_bf16 v[48:51], v[230:233], v[202:205], v[48:51]
	v_mfma_f32_16x16x32_bf16 v[52:55], v[234:237], v[202:205], v[52:55]
	v_add_u32_e32 v125, s24, v173
	v_add_u32_e32 v126, s25, v173
	v_mfma_f32_16x16x32_bf16 v[0:3], v[210:213], v[206:209], v[0:3]
	v_mfma_f32_16x16x32_bf16 v[4:7], v[214:217], v[206:209], v[4:7]
	v_mfma_f32_16x16x32_bf16 v[8:11], v[218:221], v[206:209], v[8:11]
	ds_write_b128 v125, v[88:91]
	ds_write_b128 v125, v[120:123] offset:1024
	ds_write_b128 v125, v[132:135] offset:2048
	ds_write_b128 v125, v[96:99] offset:3072
	ds_write_b128 v125, v[100:103] offset:4096
	ds_write_b128 v125, v[104:107] offset:5120
	ds_write_b128 v125, v[108:111] offset:6144
	v_mfma_f32_16x16x32_bf16 v[12:15], v[222:225], v[206:209], v[12:15]
	s_waitcnt lgkmcnt(0)
	s_barrier
	v_mfma_f32_16x16x32_bf16 v[16:19], v[226:229], v[206:209], v[16:19]
	v_mfma_f32_16x16x32_bf16 v[20:23], v[230:233], v[206:209], v[20:23]
	v_mfma_f32_16x16x32_bf16 v[24:27], v[234:237], v[206:209], v[24:27]
	s_add_i32 s4, s4, s23
	s_ashr_i32 s19, s4, 9
	s_cmp_lg_u32 s19, 1
	v_or_b32_e32 v118, s4, v175
	v_ashrrev_i32_e32 v119, 31, v118
	s_cselect_b64 s[4:5], -1, 0
	v_mov_b32_e32 v160, v118
	v_add_u32_e32 v116, 0xfffffe00, v118
	v_mov_b32_e32 v117, v161
	s_andn2_b64 vcc, exec, s[46:47]
	v_cndmask_b32_e64 v127, 0, 1, s[46:47]
	s_nop 1
	v_cmp_ne_u32_e64 s[40:41], 1, v127
	v_cndmask_b32_e64 v127, 0, 1, s[58:59]
	s_nop 1
	v_cmp_ne_u32_e64 s[38:39], 1, v127
	s_cbranch_vccnz .LBB0_886
	ds_read_b128 v[108:111], v126 offset:7168
	ds_read_b128 v[104:107], v126 offset:14336
	ds_read_b128 v[100:103], v126 offset:21504
	ds_read_b128 v[92:95], v126 offset:28672
	ds_read_b128 v[112:115], v174
	ds_read_b128 v[96:99], v126 offset:35840
	ds_read_b128 v[88:91], v126 offset:43008
	ds_read_b128 v[84:87], v126 offset:50176
	s_mov_b64 s[8:9], 0x10000
	s_and_b64 vcc, exec, s[38:39]
	v_lshl_add_u64 v[120:121], v[144:145], 0, s[8:9]
	s_cbranch_vccnz .LBB0_874
	v_lshl_add_u64 v[122:123], v[120:121], 3, s[44:45]
	global_load_dwordx2 v[122:123], v[122:123], off
	s_waitcnt vmcnt(0)
	v_pk_mul_f32 v[122:123], v[122:123], s[96:97] op_sel_hi:[1,0]
	s_nop 0
	v_fma_f32 v123, -v122, v122, v123
	v_max_f32_e32 v123, 0, v123
	v_add_f32_e32 v123, 0x3727c5ac, v123
	v_mul_f32_e32 v124, 0x4f800000, v123
	v_cmp_gt_f32_e32 vcc, s97, v123
	s_nop 1
	v_cndmask_b32_e32 v123, v123, v124, vcc
	v_sqrt_f32_e32 v124, v123
	s_nop 0
	v_add_u32_e32 v127, -1, v124
	v_add_u32_e32 v128, 1, v124
	v_fma_f32 v129, -v127, v124, v123
	v_fma_f32 v130, -v128, v124, v123
	v_cmp_ge_f32_e64 s[42:43], 0, v129
	s_nop 1
	v_cndmask_b32_e64 v124, v124, v127, s[42:43]
	v_cmp_lt_f32_e64 s[42:43], 0, v130
	s_nop 1
	v_cndmask_b32_e64 v124, v124, v128, s[42:43]
	v_mul_f32_e32 v127, 0x37800000, v124
	v_cndmask_b32_e32 v124, v124, v127, vcc
	v_cmp_class_f32_e32 vcc, v123, v248
	s_nop 1
	v_cndmask_b32_e32 v123, v124, v123, vcc
	v_div_scale_f32 v124, s[8:9], v123, v123, 1.0
	v_rcp_f32_e32 v127, v124
	v_div_scale_f32 v128, vcc, 1.0, v123, 1.0
	v_fma_f32 v129, -v124, v127, 1.0
	v_fmac_f32_e32 v127, v129, v127
	v_mul_f32_e32 v129, v128, v127
	v_fma_f32 v130, -v124, v129, v128
	v_fmac_f32_e32 v129, v130, v127
	v_fma_f32 v124, -v124, v129, v128
	v_div_fmas_f32 v124, v124, v127, v129
	v_div_fixup_f32 v124, v124, v123, 1.0
	s_branch .LBB0_875
